# down-GEMM residual epilogue de-serialised: four residual loads per 16-row block issued together, counted vmcnt waits instead of vmcnt(0) per quad
# speedup vs baseline: 1.0095x; 1.0095x over previous
; __device__ __forceinline__ unsigned cvt_pk_bf16(float lo, float hi) { unsigned r; asm volatile("v_cvt_pk_bf16_f32 %0, %1, %2" : "=v"(r) : "v"(lo), "v"(hi)); return r; }
;     __device__ __forceinline__ void operator()(const f32x4 (&acc)[2][2][4][2], const Unit& u, int wr, int wc, int fr, int fq) const {
;     ...
;                 const size_t off = (size_t)row * 1024 + col0;
;                 float sq = 0.f;
; #pragma unroll
;                 for (int bj = 0; bj < 2; ++bj)
; #pragma unroll
;                     for (int n = 0; n < 2; ++n) {
;                         const f32x4 b = *(const f32x4*)(base + off + bj * HALF + n * 16); const f32x4 o = b + acc[ai][bj][m][n];
;                         *(f32x4*)(out + off + bj * HALF + n * 16) = o;
;                         if (xn) { sq += (o[0] * o[0] + o[1] * o[1]) + (o[2] * o[2] + o[3] * o[3]); const f32x4 og = o * gv[bj][n];
;                             ::u32x2 w; w.x = cvt_pk_bf16(og[0], og[1]); w.y = cvt_pk_bf16(og[2], og[3]); *(::u32x2*)(xn + off + bj * HALF + n * 16) = w; }
;                     }
;                 if (xn) { sq += __shfl_xor(sq, 16); sq += __shfl_xor(sq, 32); if (fq == 0) atomicAdd(ss + row, sq); }
.LBB0_794:
	v_lshl_add_u32 v168, s28, 8, v174
	v_ashrrev_i32_e32 v169, 31, v168
	v_lshlrev_b64 v[170:171], 10, v[168:169]
	v_readlane_b32 s44, v249, 0
	v_lshl_add_u64 v[172:173], v[170:171], 0, v[152:153]
	v_readlane_b32 s46, v249, 2
	v_readlane_b32 s47, v249, 3
	s_and_b64 vcc, exec, s[42:43]
	s_mov_b64 s[14:15], -1
	v_lshl_add_u64 v[170:171], v[172:173], 2, s[46:47]
	global_load_dwordx4 v[178:181], v[170:171], off
	global_load_dwordx4 v[212:215], v[170:171], off offset:64
	global_load_dwordx4 v[216:219], v[170:171], off offset:512
	global_load_dwordx4 v[220:223], v[170:171], off offset:576
	v_readlane_b32 s45, v249, 1
	v_readlane_b32 s48, v249, 4
	v_readlane_b32 s49, v249, 5
	v_readlane_b32 s50, v249, 6
	v_readlane_b32 s51, v249, 7
	s_waitcnt vmcnt(3)
	v_pk_add_f32 v[144:145], v[144:145], v[180:181]
	v_pk_add_f32 v[142:143], v[142:143], v[178:179]
	global_store_dwordx4 v[170:171], v[142:145], off
	s_cbranch_vccnz .LBB0_798
	v_readlane_b32 s14, v245, 28
	v_mul_f32_e32 v178, v143, v143
	v_readlane_b32 s15, v245, 29
	v_fmac_f32_e32 v178, v142, v142
	v_mul_f32_e32 v179, v145, v145
	v_pk_mul_f32 v[142:143], v[56:57], v[142:143]
	v_lshl_add_u64 v[172:173], v[172:173], 1, s[14:15]
	v_fmac_f32_e32 v179, v144, v144
	v_pk_mul_f32 v[144:145], v[58:59], v[144:145]
	v_cvt_pk_bf16_f32 v142, v142, v143
	v_add_f32_e32 v178, v178, v179
	v_cvt_pk_bf16_f32 v143, v144, v145
	global_store_dwordx2 v[172:173], v[142:143], off
	s_waitcnt vmcnt(4)
	v_pk_add_f32 v[142:143], v[138:139], v[212:213]
	v_pk_add_f32 v[144:145], v[140:141], v[214:215]
	v_mul_f32_e32 v179, v143, v143
	global_store_dwordx4 v[170:171], v[142:145], off offset:64
	v_fmac_f32_e32 v179, v142, v142
	v_mul_f32_e32 v180, v145, v145
	v_pk_mul_f32 v[142:143], v[52:53], v[142:143]
	v_fmac_f32_e32 v180, v144, v144
	v_pk_mul_f32 v[144:145], v[54:55], v[144:145]
	v_cvt_pk_bf16_f32 v142, v142, v143
	v_add_f32_e32 v179, v179, v180
	v_cvt_pk_bf16_f32 v143, v144, v145
	global_store_dwordx2 v[172:173], v[142:143], off offset:32
	v_add_f32_e32 v178, v178, v179
	s_waitcnt vmcnt(5)
	v_pk_add_f32 v[142:143], v[134:135], v[216:217]
	v_pk_add_f32 v[144:145], v[136:137], v[218:219]
	v_mul_f32_e32 v179, v143, v143
	global_store_dwordx4 v[170:171], v[142:145], off offset:512
	v_fmac_f32_e32 v179, v142, v142
	v_mul_f32_e32 v180, v145, v145
	v_pk_mul_f32 v[142:143], v[48:49], v[142:143]
	v_fmac_f32_e32 v180, v144, v144
	v_pk_mul_f32 v[144:145], v[50:51], v[144:145]
	v_cvt_pk_bf16_f32 v142, v142, v143
	v_add_f32_e32 v179, v179, v180
	v_cvt_pk_bf16_f32 v143, v144, v145
	global_store_dwordx2 v[172:173], v[142:143], off offset:256
	v_add_f32_e32 v182, v178, v179
	s_waitcnt vmcnt(6)
	v_pk_add_f32 v[144:145], v[132:133], v[222:223]
	v_pk_add_f32 v[142:143], v[130:131], v[220:221]
	global_store_dwordx4 v[170:171], v[142:145], off offset:576
	v_pk_mul_f32 v[180:181], v[36:37], v[142:143]
	v_pk_mul_f32 v[178:179], v[38:39], v[144:145]
	v_mul_f32_e32 v143, v143, v143
	v_fmac_f32_e32 v143, v142, v142
	v_mul_f32_e32 v142, v145, v145
	v_fmac_f32_e32 v142, v144, v144
	v_and_b32_e32 v144, 64, v190
	v_add_f32_e32 v142, v143, v142
	v_xor_b32_e32 v143, 16, v190
	v_add_u32_e32 v144, 64, v144
	v_cmp_lt_i32_e32 vcc, v143, v144
	v_add_f32_e32 v142, v182, v142
	v_cvt_pk_bf16_f32 v180, v180, v181
	v_cvt_pk_bf16_f32 v181, v178, v179
	global_store_dwordx2 v[172:173], v[180:181], off offset:288
	v_cndmask_b32_e32 v143, v190, v143, vcc
	v_lshlrev_b32_e32 v143, 2, v143
	ds_bpermute_b32 v143, v143, v142
	s_waitcnt lgkmcnt(0)
	v_add_f32_e32 v142, v142, v143
	v_xor_b32_e32 v143, 32, v190
	v_cmp_lt_i32_e32 vcc, v143, v144
	s_nop 1
	v_cndmask_b32_e32 v143, v190, v143, vcc
	v_lshlrev_b32_e32 v143, 2, v143
	ds_bpermute_b32 v143, v143, v142
	s_and_saveexec_b64 s[14:15], s[38:39]
	s_cbranch_execz .LBB0_797
	v_readlane_b32 s16, v245, 42
	v_readlane_b32 s17, v245, 43
	s_waitcnt lgkmcnt(0)
	v_add_f32_e32 v142, v142, v143
	v_lshl_add_u64 v[144:145], v[168:169], 2, s[16:17]
	global_atomic_add_f32 v[144:145], v142, off

; __device__ __forceinline__ unsigned cvt_pk_bf16(float lo, float hi) { unsigned r; asm volatile("v_cvt_pk_bf16_f32 %0, %1, %2" : "=v"(r) : "v"(lo), "v"(hi)); return r; }
;     __device__ __forceinline__ void operator()(const f32x4 (&acc)[2][2][4][2], const Unit& u, int wr, int wc, int fr, int fq) const {
;     ...
;                 const size_t off = (size_t)row * 1024 + col0;
;                 float sq = 0.f;
; #pragma unroll
;                 for (int bj = 0; bj < 2; ++bj)
; #pragma unroll
;                     for (int n = 0; n < 2; ++n) {
;                         const f32x4 b = *(const f32x4*)(base + off + bj * HALF + n * 16); const f32x4 o = b + acc[ai][bj][m][n];
;                         *(f32x4*)(out + off + bj * HALF + n * 16) = o;
;                         if (xn) { sq += (o[0] * o[0] + o[1] * o[1]) + (o[2] * o[2] + o[3] * o[3]); const f32x4 og = o * gv[bj][n];
;                             ::u32x2 w; w.x = cvt_pk_bf16(og[0], og[1]); w.y = cvt_pk_bf16(og[2], og[3]); *(::u32x2*)(xn + off + bj * HALF + n * 16) = w; }
;                     }
;                 if (xn) { sq += __shfl_xor(sq, 16); sq += __shfl_xor(sq, 32); if (fq == 0) atomicAdd(ss + row, sq); }
.LBB0_798:
	s_andn2_b64 vcc, exec, s[14:15]
	s_cbranch_vccnz .LBB0_800
	s_waitcnt lgkmcnt(0)
	s_waitcnt vmcnt(3)
	v_pk_add_f32 v[140:141], v[140:141], v[214:215]
	v_pk_add_f32 v[138:139], v[138:139], v[212:213]
	global_store_dwordx4 v[170:171], v[138:141], off offset:64
	s_waitcnt vmcnt(3)
	v_pk_add_f32 v[136:137], v[136:137], v[218:219]
	v_pk_add_f32 v[134:135], v[134:135], v[216:217]
	global_store_dwordx4 v[170:171], v[134:137], off offset:512
	s_waitcnt vmcnt(3)
	v_pk_add_f32 v[132:133], v[132:133], v[222:223]
	v_pk_add_f32 v[130:131], v[130:131], v[220:221]
	global_store_dwordx4 v[170:171], v[130:133], off offset:576
.LBB0_800:
	s_nop 1
	v_or_b32_e32 v132, 16, v168
	v_ashrrev_i32_e32 v133, 31, v132
	v_lshlrev_b64 v[130:131], 10, v[132:133]
	v_readlane_b32 s44, v249, 0
	v_lshl_add_u64 v[134:135], v[130:131], 0, v[152:153]
	v_readlane_b32 s46, v249, 2
	v_readlane_b32 s47, v249, 3
	s_and_b64 vcc, exec, s[42:43]
	s_mov_b64 s[14:15], -1
	v_lshl_add_u64 v[130:131], v[134:135], 2, s[46:47]
	global_load_dwordx4 v[136:139], v[130:131], off
	global_load_dwordx4 v[212:215], v[130:131], off offset:64
	global_load_dwordx4 v[216:219], v[130:131], off offset:512
	global_load_dwordx4 v[220:223], v[130:131], off offset:576
	v_readlane_b32 s45, v249, 1
	v_readlane_b32 s48, v249, 4
	v_readlane_b32 s49, v249, 5
	v_readlane_b32 s50, v249, 6
	v_readlane_b32 s51, v249, 7
	s_waitcnt vmcnt(3)
	v_pk_add_f32 v[126:127], v[126:127], v[138:139]
	v_pk_add_f32 v[124:125], v[124:125], v[136:137]
	global_store_dwordx4 v[130:131], v[124:127], off
	s_cbranch_vccnz .LBB0_804
	v_readlane_b32 s14, v245, 28
	v_mul_f32_e32 v136, v125, v125
	v_readlane_b32 s15, v245, 29
	v_fmac_f32_e32 v136, v124, v124
	v_mul_f32_e32 v137, v127, v127
	v_pk_mul_f32 v[124:125], v[56:57], v[124:125]
	v_lshl_add_u64 v[134:135], v[134:135], 1, s[14:15]
	v_fmac_f32_e32 v137, v126, v126
	v_pk_mul_f32 v[126:127], v[58:59], v[126:127]
	v_cvt_pk_bf16_f32 v124, v124, v125
	v_add_f32_e32 v136, v136, v137
	v_cvt_pk_bf16_f32 v125, v126, v127
	global_store_dwordx2 v[134:135], v[124:125], off
	s_waitcnt vmcnt(4)
	v_pk_add_f32 v[124:125], v[120:121], v[212:213]
	v_pk_add_f32 v[126:127], v[122:123], v[214:215]
	v_mul_f32_e32 v137, v125, v125
	global_store_dwordx4 v[130:131], v[124:127], off offset:64
	v_fmac_f32_e32 v137, v124, v124
	v_mul_f32_e32 v138, v127, v127
	v_pk_mul_f32 v[124:125], v[52:53], v[124:125]
	v_fmac_f32_e32 v138, v126, v126
	v_pk_mul_f32 v[126:127], v[54:55], v[126:127]
	v_cvt_pk_bf16_f32 v124, v124, v125
	v_add_f32_e32 v137, v137, v138
	v_cvt_pk_bf16_f32 v125, v126, v127
	global_store_dwordx2 v[134:135], v[124:125], off offset:32
	v_add_f32_e32 v136, v136, v137
	s_waitcnt vmcnt(5)
	v_pk_add_f32 v[124:125], v[116:117], v[216:217]
	v_pk_add_f32 v[126:127], v[118:119], v[218:219]
	v_mul_f32_e32 v137, v125, v125
	global_store_dwordx4 v[130:131], v[124:127], off offset:512
	v_fmac_f32_e32 v137, v124, v124
	v_mul_f32_e32 v138, v127, v127
	v_pk_mul_f32 v[124:125], v[48:49], v[124:125]
	v_fmac_f32_e32 v138, v126, v126
	v_pk_mul_f32 v[126:127], v[50:51], v[126:127]
	v_cvt_pk_bf16_f32 v124, v124, v125
	v_add_f32_e32 v137, v137, v138
	v_cvt_pk_bf16_f32 v125, v126, v127
	global_store_dwordx2 v[134:135], v[124:125], off offset:256
	v_add_f32_e32 v140, v136, v137
	s_waitcnt vmcnt(6)
	v_pk_add_f32 v[126:127], v[114:115], v[222:223]
	v_pk_add_f32 v[124:125], v[112:113], v[220:221]
	global_store_dwordx4 v[130:131], v[124:127], off offset:576
	v_pk_mul_f32 v[138:139], v[36:37], v[124:125]
	v_pk_mul_f32 v[136:137], v[38:39], v[126:127]
	v_mul_f32_e32 v125, v125, v125
	v_fmac_f32_e32 v125, v124, v124
	v_mul_f32_e32 v124, v127, v127
	v_fmac_f32_e32 v124, v126, v126
	v_and_b32_e32 v126, 64, v190
	v_add_f32_e32 v124, v125, v124
	v_xor_b32_e32 v125, 16, v190
	v_add_u32_e32 v126, 64, v126
	v_cmp_lt_i32_e32 vcc, v125, v126
	v_add_f32_e32 v124, v140, v124
	v_cvt_pk_bf16_f32 v138, v138, v139
	v_cvt_pk_bf16_f32 v139, v136, v137
	global_store_dwordx2 v[134:135], v[138:139], off offset:288
	v_cndmask_b32_e32 v125, v190, v125, vcc
	v_lshlrev_b32_e32 v125, 2, v125
	ds_bpermute_b32 v125, v125, v124
	s_waitcnt lgkmcnt(0)
	v_add_f32_e32 v124, v124, v125
	v_xor_b32_e32 v125, 32, v190
	v_cmp_lt_i32_e32 vcc, v125, v126
	s_nop 1
	v_cndmask_b32_e32 v125, v190, v125, vcc
	v_lshlrev_b32_e32 v125, 2, v125
	ds_bpermute_b32 v125, v125, v124
	s_and_saveexec_b64 s[14:15], s[38:39]
	s_cbranch_execz .LBB0_803
	v_readlane_b32 s16, v245, 42
	v_readlane_b32 s17, v245, 43
	s_waitcnt lgkmcnt(0)
	v_add_f32_e32 v124, v124, v125
	v_lshl_add_u64 v[126:127], v[132:133], 2, s[16:17]
	global_atomic_add_f32 v[126:127], v124, off

; __device__ __forceinline__ unsigned cvt_pk_bf16(float lo, float hi) { unsigned r; asm volatile("v_cvt_pk_bf16_f32 %0, %1, %2" : "=v"(r) : "v"(lo), "v"(hi)); return r; }
;     __device__ __forceinline__ void operator()(const f32x4 (&acc)[2][2][4][2], const Unit& u, int wr, int wc, int fr, int fq) const {
;     ...
;                 const size_t off = (size_t)row * 1024 + col0;
;                 float sq = 0.f;
; #pragma unroll
;                 for (int bj = 0; bj < 2; ++bj)
; #pragma unroll
;                     for (int n = 0; n < 2; ++n) {
;                         const f32x4 b = *(const f32x4*)(base + off + bj * HALF + n * 16); const f32x4 o = b + acc[ai][bj][m][n];
;                         *(f32x4*)(out + off + bj * HALF + n * 16) = o;
;                         if (xn) { sq += (o[0] * o[0] + o[1] * o[1]) + (o[2] * o[2] + o[3] * o[3]); const f32x4 og = o * gv[bj][n];
;                             ::u32x2 w; w.x = cvt_pk_bf16(og[0], og[1]); w.y = cvt_pk_bf16(og[2], og[3]); *(::u32x2*)(xn + off + bj * HALF + n * 16) = w; }
;                     }
;                 if (xn) { sq += __shfl_xor(sq, 16); sq += __shfl_xor(sq, 32); if (fq == 0) atomicAdd(ss + row, sq); }
.LBB0_804:
	s_andn2_b64 vcc, exec, s[14:15]
	s_cbranch_vccnz .LBB0_806
	s_waitcnt lgkmcnt(0)
	s_waitcnt vmcnt(3)
	v_pk_add_f32 v[122:123], v[122:123], v[214:215]
	v_pk_add_f32 v[120:121], v[120:121], v[212:213]
	global_store_dwordx4 v[130:131], v[120:123], off offset:64
	s_waitcnt vmcnt(3)
	v_pk_add_f32 v[118:119], v[118:119], v[218:219]
	v_pk_add_f32 v[116:117], v[116:117], v[216:217]
	global_store_dwordx4 v[130:131], v[116:119], off offset:512
	s_waitcnt vmcnt(3)
	v_pk_add_f32 v[114:115], v[114:115], v[222:223]
	v_pk_add_f32 v[112:113], v[112:113], v[220:221]
	global_store_dwordx4 v[130:131], v[112:115], off offset:576
.LBB0_806:
	s_nop 1
	v_or_b32_e32 v114, 32, v168
	v_ashrrev_i32_e32 v115, 31, v114
	v_lshlrev_b64 v[112:113], 10, v[114:115]
	v_readlane_b32 s44, v249, 0
	v_lshl_add_u64 v[116:117], v[112:113], 0, v[152:153]
	v_readlane_b32 s46, v249, 2
	v_readlane_b32 s47, v249, 3
	s_and_b64 vcc, exec, s[42:43]
	s_mov_b64 s[14:15], -1
	v_lshl_add_u64 v[112:113], v[116:117], 2, s[46:47]
	global_load_dwordx4 v[118:121], v[112:113], off
	global_load_dwordx4 v[212:215], v[112:113], off offset:64
	global_load_dwordx4 v[216:219], v[112:113], off offset:512
	global_load_dwordx4 v[220:223], v[112:113], off offset:576
	v_readlane_b32 s45, v249, 1
	v_readlane_b32 s48, v249, 4
	v_readlane_b32 s49, v249, 5
	v_readlane_b32 s50, v249, 6
	v_readlane_b32 s51, v249, 7
	s_waitcnt vmcnt(3)
	v_pk_add_f32 v[110:111], v[110:111], v[120:121]
	v_pk_add_f32 v[108:109], v[108:109], v[118:119]
	global_store_dwordx4 v[112:113], v[108:111], off
	s_cbranch_vccnz .LBB0_810
	v_readlane_b32 s14, v245, 28
	v_mul_f32_e32 v118, v109, v109
	v_readlane_b32 s15, v245, 29
	v_fmac_f32_e32 v118, v108, v108
	v_mul_f32_e32 v119, v111, v111
	v_pk_mul_f32 v[108:109], v[56:57], v[108:109]
	v_lshl_add_u64 v[116:117], v[116:117], 1, s[14:15]
	v_fmac_f32_e32 v119, v110, v110
	v_pk_mul_f32 v[110:111], v[58:59], v[110:111]
	v_cvt_pk_bf16_f32 v108, v108, v109
	v_add_f32_e32 v118, v118, v119
	v_cvt_pk_bf16_f32 v109, v110, v111
	global_store_dwordx2 v[116:117], v[108:109], off
	s_waitcnt vmcnt(4)
	v_pk_add_f32 v[108:109], v[104:105], v[212:213]
	v_pk_add_f32 v[110:111], v[106:107], v[214:215]
	v_mul_f32_e32 v119, v109, v109
	global_store_dwordx4 v[112:113], v[108:111], off offset:64
	v_fmac_f32_e32 v119, v108, v108
	v_mul_f32_e32 v120, v111, v111
	v_pk_mul_f32 v[108:109], v[52:53], v[108:109]
	v_fmac_f32_e32 v120, v110, v110
	v_pk_mul_f32 v[110:111], v[54:55], v[110:111]
	v_cvt_pk_bf16_f32 v108, v108, v109
	v_add_f32_e32 v119, v119, v120
	v_cvt_pk_bf16_f32 v109, v110, v111
	global_store_dwordx2 v[116:117], v[108:109], off offset:32
	v_add_f32_e32 v118, v118, v119
	s_waitcnt vmcnt(5)
	v_pk_add_f32 v[108:109], v[100:101], v[216:217]
	v_pk_add_f32 v[110:111], v[102:103], v[218:219]
	v_mul_f32_e32 v119, v109, v109
	global_store_dwordx4 v[112:113], v[108:111], off offset:512
	v_fmac_f32_e32 v119, v108, v108
	v_mul_f32_e32 v120, v111, v111
	v_pk_mul_f32 v[108:109], v[48:49], v[108:109]
	v_fmac_f32_e32 v120, v110, v110
	v_pk_mul_f32 v[110:111], v[50:51], v[110:111]
	v_cvt_pk_bf16_f32 v108, v108, v109
	v_add_f32_e32 v119, v119, v120
	v_cvt_pk_bf16_f32 v109, v110, v111
	global_store_dwordx2 v[116:117], v[108:109], off offset:256
	v_add_f32_e32 v122, v118, v119
	s_waitcnt vmcnt(6)
	v_pk_add_f32 v[110:111], v[98:99], v[222:223]
	v_pk_add_f32 v[108:109], v[96:97], v[220:221]
	global_store_dwordx4 v[112:113], v[108:111], off offset:576
	v_pk_mul_f32 v[120:121], v[36:37], v[108:109]
	v_pk_mul_f32 v[118:119], v[38:39], v[110:111]
	v_mul_f32_e32 v109, v109, v109
	v_fmac_f32_e32 v109, v108, v108
	v_mul_f32_e32 v108, v111, v111
	v_fmac_f32_e32 v108, v110, v110
	v_and_b32_e32 v110, 64, v190
	v_add_f32_e32 v108, v109, v108
	v_xor_b32_e32 v109, 16, v190
	v_add_u32_e32 v110, 64, v110
	v_cmp_lt_i32_e32 vcc, v109, v110
	v_add_f32_e32 v108, v122, v108
	v_cvt_pk_bf16_f32 v120, v120, v121
	v_cvt_pk_bf16_f32 v121, v118, v119
	global_store_dwordx2 v[116:117], v[120:121], off offset:288
	v_cndmask_b32_e32 v109, v190, v109, vcc
	v_lshlrev_b32_e32 v109, 2, v109
	ds_bpermute_b32 v109, v109, v108
	s_waitcnt lgkmcnt(0)
	v_add_f32_e32 v108, v108, v109
	v_xor_b32_e32 v109, 32, v190
	v_cmp_lt_i32_e32 vcc, v109, v110
	s_nop 1
	v_cndmask_b32_e32 v109, v190, v109, vcc
	v_lshlrev_b32_e32 v109, 2, v109
	ds_bpermute_b32 v109, v109, v108
	s_and_saveexec_b64 s[14:15], s[38:39]
	s_cbranch_execz .LBB0_809
	v_readlane_b32 s16, v245, 42
	v_readlane_b32 s17, v245, 43
	s_waitcnt lgkmcnt(0)
	v_add_f32_e32 v108, v108, v109
	v_lshl_add_u64 v[110:111], v[114:115], 2, s[16:17]
	global_atomic_add_f32 v[110:111], v108, off

; __device__ __forceinline__ unsigned cvt_pk_bf16(float lo, float hi) { unsigned r; asm volatile("v_cvt_pk_bf16_f32 %0, %1, %2" : "=v"(r) : "v"(lo), "v"(hi)); return r; }
;     __device__ __forceinline__ void operator()(const f32x4 (&acc)[2][2][4][2], const Unit& u, int wr, int wc, int fr, int fq) const {
;     ...
;                 const size_t off = (size_t)row * 1024 + col0;
;                 float sq = 0.f;
; #pragma unroll
;                 for (int bj = 0; bj < 2; ++bj)
; #pragma unroll
;                     for (int n = 0; n < 2; ++n) {
;                         const f32x4 b = *(const f32x4*)(base + off + bj * HALF + n * 16); const f32x4 o = b + acc[ai][bj][m][n];
;                         *(f32x4*)(out + off + bj * HALF + n * 16) = o;
;                         if (xn) { sq += (o[0] * o[0] + o[1] * o[1]) + (o[2] * o[2] + o[3] * o[3]); const f32x4 og = o * gv[bj][n];
;                             ::u32x2 w; w.x = cvt_pk_bf16(og[0], og[1]); w.y = cvt_pk_bf16(og[2], og[3]); *(::u32x2*)(xn + off + bj * HALF + n * 16) = w; }
;                     }
;                 if (xn) { sq += __shfl_xor(sq, 16); sq += __shfl_xor(sq, 32); if (fq == 0) atomicAdd(ss + row, sq); }
.LBB0_810:
	s_andn2_b64 vcc, exec, s[14:15]
	s_cbranch_vccnz .LBB0_812
	s_waitcnt lgkmcnt(0)
	s_waitcnt vmcnt(3)
	v_pk_add_f32 v[106:107], v[106:107], v[214:215]
	v_pk_add_f32 v[104:105], v[104:105], v[212:213]
	global_store_dwordx4 v[112:113], v[104:107], off offset:64
	s_waitcnt vmcnt(3)
	v_pk_add_f32 v[102:103], v[102:103], v[218:219]
	v_pk_add_f32 v[100:101], v[100:101], v[216:217]
	global_store_dwordx4 v[112:113], v[100:103], off offset:512
	s_waitcnt vmcnt(3)
	v_pk_add_f32 v[98:99], v[98:99], v[222:223]
	v_pk_add_f32 v[96:97], v[96:97], v[220:221]
	global_store_dwordx4 v[112:113], v[96:99], off offset:576
.LBB0_812:
	s_nop 1
	v_or_b32_e32 v98, 48, v168
	v_ashrrev_i32_e32 v99, 31, v98
	v_lshlrev_b64 v[96:97], 10, v[98:99]
	v_readlane_b32 s44, v249, 0
	v_lshl_add_u64 v[100:101], v[96:97], 0, v[152:153]
	v_readlane_b32 s46, v249, 2
	v_readlane_b32 s47, v249, 3
	s_and_b64 vcc, exec, s[42:43]
	s_mov_b64 s[14:15], -1
	v_lshl_add_u64 v[96:97], v[100:101], 2, s[46:47]
	global_load_dwordx4 v[102:105], v[96:97], off
	global_load_dwordx4 v[212:215], v[96:97], off offset:64
	global_load_dwordx4 v[216:219], v[96:97], off offset:512
	global_load_dwordx4 v[220:223], v[96:97], off offset:576
	v_readlane_b32 s45, v249, 1
	v_readlane_b32 s48, v249, 4
	v_readlane_b32 s49, v249, 5
	v_readlane_b32 s50, v249, 6
	v_readlane_b32 s51, v249, 7
	s_waitcnt vmcnt(3)
	v_pk_add_f32 v[94:95], v[94:95], v[104:105]
	v_pk_add_f32 v[92:93], v[92:93], v[102:103]
	global_store_dwordx4 v[96:97], v[92:95], off
	s_cbranch_vccnz .LBB0_816
	v_readlane_b32 s14, v245, 28
	v_mul_f32_e32 v102, v93, v93
	v_readlane_b32 s15, v245, 29
	v_fmac_f32_e32 v102, v92, v92
	v_mul_f32_e32 v103, v95, v95
	v_pk_mul_f32 v[92:93], v[56:57], v[92:93]
	v_lshl_add_u64 v[100:101], v[100:101], 1, s[14:15]
	v_fmac_f32_e32 v103, v94, v94
	v_pk_mul_f32 v[94:95], v[58:59], v[94:95]
	v_cvt_pk_bf16_f32 v92, v92, v93
	v_add_f32_e32 v102, v102, v103
	v_cvt_pk_bf16_f32 v93, v94, v95
	global_store_dwordx2 v[100:101], v[92:93], off
	s_waitcnt vmcnt(4)
	v_pk_add_f32 v[92:93], v[88:89], v[212:213]
	v_pk_add_f32 v[94:95], v[90:91], v[214:215]
	v_mul_f32_e32 v103, v93, v93
	global_store_dwordx4 v[96:97], v[92:95], off offset:64
	v_fmac_f32_e32 v103, v92, v92
	v_mul_f32_e32 v104, v95, v95
	v_pk_mul_f32 v[92:93], v[52:53], v[92:93]
	v_fmac_f32_e32 v104, v94, v94
	v_pk_mul_f32 v[94:95], v[54:55], v[94:95]
	v_cvt_pk_bf16_f32 v92, v92, v93
	v_add_f32_e32 v103, v103, v104
	v_cvt_pk_bf16_f32 v93, v94, v95
	global_store_dwordx2 v[100:101], v[92:93], off offset:32
	v_add_f32_e32 v102, v102, v103
	s_waitcnt vmcnt(5)
	v_pk_add_f32 v[92:93], v[84:85], v[216:217]
	v_pk_add_f32 v[94:95], v[86:87], v[218:219]
	v_mul_f32_e32 v103, v93, v93
	global_store_dwordx4 v[96:97], v[92:95], off offset:512
	v_fmac_f32_e32 v103, v92, v92
	v_mul_f32_e32 v104, v95, v95
	v_pk_mul_f32 v[92:93], v[48:49], v[92:93]
	v_fmac_f32_e32 v104, v94, v94
	v_pk_mul_f32 v[94:95], v[50:51], v[94:95]
	v_cvt_pk_bf16_f32 v92, v92, v93
	v_add_f32_e32 v103, v103, v104
	v_cvt_pk_bf16_f32 v93, v94, v95
	global_store_dwordx2 v[100:101], v[92:93], off offset:256
	v_add_f32_e32 v106, v102, v103
	s_waitcnt vmcnt(6)
	v_pk_add_f32 v[94:95], v[82:83], v[222:223]
	v_pk_add_f32 v[92:93], v[80:81], v[220:221]
	global_store_dwordx4 v[96:97], v[92:95], off offset:576
	v_pk_mul_f32 v[104:105], v[36:37], v[92:93]
	v_pk_mul_f32 v[102:103], v[38:39], v[94:95]
	v_mul_f32_e32 v93, v93, v93
	v_fmac_f32_e32 v93, v92, v92
	v_mul_f32_e32 v92, v95, v95
	v_fmac_f32_e32 v92, v94, v94
	v_and_b32_e32 v94, 64, v190
	v_add_f32_e32 v92, v93, v92
	v_xor_b32_e32 v93, 16, v190
	v_add_u32_e32 v94, 64, v94
	v_cmp_lt_i32_e32 vcc, v93, v94
	v_add_f32_e32 v92, v106, v92
	v_cvt_pk_bf16_f32 v104, v104, v105
	v_cvt_pk_bf16_f32 v105, v102, v103
	global_store_dwordx2 v[100:101], v[104:105], off offset:288
	v_cndmask_b32_e32 v93, v190, v93, vcc
	v_lshlrev_b32_e32 v93, 2, v93
	ds_bpermute_b32 v93, v93, v92
	s_waitcnt lgkmcnt(0)
	v_add_f32_e32 v92, v92, v93
	v_xor_b32_e32 v93, 32, v190
	v_cmp_lt_i32_e32 vcc, v93, v94
	s_nop 1
	v_cndmask_b32_e32 v93, v190, v93, vcc
	v_lshlrev_b32_e32 v93, 2, v93
	ds_bpermute_b32 v93, v93, v92
	s_and_saveexec_b64 s[14:15], s[38:39]
	s_cbranch_execz .LBB0_815
	v_readlane_b32 s16, v245, 42
	v_readlane_b32 s17, v245, 43
	s_waitcnt lgkmcnt(0)
	v_add_f32_e32 v92, v92, v93
	v_lshl_add_u64 v[94:95], v[98:99], 2, s[16:17]
	global_atomic_add_f32 v[94:95], v92, off

; __device__ __forceinline__ unsigned cvt_pk_bf16(float lo, float hi) { unsigned r; asm volatile("v_cvt_pk_bf16_f32 %0, %1, %2" : "=v"(r) : "v"(lo), "v"(hi)); return r; }
;     __device__ __forceinline__ void operator()(const f32x4 (&acc)[2][2][4][2], const Unit& u, int wr, int wc, int fr, int fq) const {
;     ...
;                 const size_t off = (size_t)row * 1024 + col0;
;                 float sq = 0.f;
; #pragma unroll
;                 for (int bj = 0; bj < 2; ++bj)
; #pragma unroll
;                     for (int n = 0; n < 2; ++n) {
;                         const f32x4 b = *(const f32x4*)(base + off + bj * HALF + n * 16); const f32x4 o = b + acc[ai][bj][m][n];
;                         *(f32x4*)(out + off + bj * HALF + n * 16) = o;
;                         if (xn) { sq += (o[0] * o[0] + o[1] * o[1]) + (o[2] * o[2] + o[3] * o[3]); const f32x4 og = o * gv[bj][n];
;                             ::u32x2 w; w.x = cvt_pk_bf16(og[0], og[1]); w.y = cvt_pk_bf16(og[2], og[3]); *(::u32x2*)(xn + off + bj * HALF + n * 16) = w; }
;                     }
;                 if (xn) { sq += __shfl_xor(sq, 16); sq += __shfl_xor(sq, 32); if (fq == 0) atomicAdd(ss + row, sq); }
.LBB0_816:
	s_andn2_b64 vcc, exec, s[14:15]
	s_cbranch_vccnz .LBB0_818
	s_waitcnt lgkmcnt(0)
	s_waitcnt vmcnt(3)
	v_pk_add_f32 v[90:91], v[90:91], v[214:215]
	v_pk_add_f32 v[88:89], v[88:89], v[212:213]
	global_store_dwordx4 v[96:97], v[88:91], off offset:64
	s_waitcnt vmcnt(3)
	v_pk_add_f32 v[86:87], v[86:87], v[218:219]
	v_pk_add_f32 v[84:85], v[84:85], v[216:217]
	global_store_dwordx4 v[96:97], v[84:87], off offset:512
	s_waitcnt vmcnt(3)
	v_pk_add_f32 v[82:83], v[82:83], v[222:223]
	v_pk_add_f32 v[80:81], v[80:81], v[220:221]
	global_store_dwordx4 v[96:97], v[80:83], off offset:576
.LBB0_818:
	s_nop 1
	v_add_u32_e32 v82, 0x80, v168
	v_ashrrev_i32_e32 v83, 31, v82
	v_lshlrev_b64 v[80:81], 10, v[82:83]
	v_readlane_b32 s44, v249, 0
	v_lshl_add_u64 v[84:85], v[80:81], 0, v[152:153]
	v_readlane_b32 s46, v249, 2
	v_readlane_b32 s47, v249, 3
	s_and_b64 vcc, exec, s[42:43]
	s_mov_b64 s[14:15], -1
	v_lshl_add_u64 v[80:81], v[84:85], 2, s[46:47]
	global_load_dwordx4 v[86:89], v[80:81], off
	global_load_dwordx4 v[212:215], v[80:81], off offset:64
	global_load_dwordx4 v[216:219], v[80:81], off offset:512
	global_load_dwordx4 v[220:223], v[80:81], off offset:576
	v_readlane_b32 s45, v249, 1
	v_readlane_b32 s48, v249, 4
	v_readlane_b32 s49, v249, 5
	v_readlane_b32 s50, v249, 6
	v_readlane_b32 s51, v249, 7
	s_waitcnt vmcnt(3)
	v_pk_add_f32 v[78:79], v[78:79], v[88:89]
	v_pk_add_f32 v[76:77], v[76:77], v[86:87]
	global_store_dwordx4 v[80:81], v[76:79], off
	s_cbranch_vccnz .LBB0_822
	v_readlane_b32 s14, v245, 28
	v_mul_f32_e32 v86, v77, v77
	v_readlane_b32 s15, v245, 29
	v_fmac_f32_e32 v86, v76, v76
	v_mul_f32_e32 v87, v79, v79
	v_pk_mul_f32 v[76:77], v[56:57], v[76:77]
	v_lshl_add_u64 v[84:85], v[84:85], 1, s[14:15]
	v_fmac_f32_e32 v87, v78, v78
	v_pk_mul_f32 v[78:79], v[58:59], v[78:79]
	v_cvt_pk_bf16_f32 v76, v76, v77
	v_add_f32_e32 v86, v86, v87
	v_cvt_pk_bf16_f32 v77, v78, v79
	global_store_dwordx2 v[84:85], v[76:77], off
	s_waitcnt vmcnt(4)
	v_pk_add_f32 v[76:77], v[72:73], v[212:213]
	v_pk_add_f32 v[78:79], v[74:75], v[214:215]
	v_mul_f32_e32 v87, v77, v77
	global_store_dwordx4 v[80:81], v[76:79], off offset:64
	v_fmac_f32_e32 v87, v76, v76
	v_mul_f32_e32 v88, v79, v79
	v_pk_mul_f32 v[76:77], v[52:53], v[76:77]
	v_fmac_f32_e32 v88, v78, v78
	v_pk_mul_f32 v[78:79], v[54:55], v[78:79]
	v_cvt_pk_bf16_f32 v76, v76, v77
	v_add_f32_e32 v87, v87, v88
	v_cvt_pk_bf16_f32 v77, v78, v79
	global_store_dwordx2 v[84:85], v[76:77], off offset:32
	v_add_f32_e32 v86, v86, v87
	s_waitcnt vmcnt(5)
	v_pk_add_f32 v[76:77], v[68:69], v[216:217]
	v_pk_add_f32 v[78:79], v[70:71], v[218:219]
	v_mul_f32_e32 v87, v77, v77
	global_store_dwordx4 v[80:81], v[76:79], off offset:512
	v_fmac_f32_e32 v87, v76, v76
	v_mul_f32_e32 v88, v79, v79
	v_pk_mul_f32 v[76:77], v[48:49], v[76:77]
	v_fmac_f32_e32 v88, v78, v78
	v_pk_mul_f32 v[78:79], v[50:51], v[78:79]
	v_cvt_pk_bf16_f32 v76, v76, v77
	v_add_f32_e32 v87, v87, v88
	v_cvt_pk_bf16_f32 v77, v78, v79
	global_store_dwordx2 v[84:85], v[76:77], off offset:256
	v_add_f32_e32 v90, v86, v87
	s_waitcnt vmcnt(6)
	v_pk_add_f32 v[78:79], v[66:67], v[222:223]
	v_pk_add_f32 v[76:77], v[64:65], v[220:221]
	global_store_dwordx4 v[80:81], v[76:79], off offset:576
	v_pk_mul_f32 v[88:89], v[36:37], v[76:77]
	v_pk_mul_f32 v[86:87], v[38:39], v[78:79]
	v_mul_f32_e32 v77, v77, v77
	v_fmac_f32_e32 v77, v76, v76
	v_mul_f32_e32 v76, v79, v79
	v_fmac_f32_e32 v76, v78, v78
	v_and_b32_e32 v78, 64, v190
	v_add_f32_e32 v76, v77, v76
	v_xor_b32_e32 v77, 16, v190
	v_add_u32_e32 v78, 64, v78
	v_cmp_lt_i32_e32 vcc, v77, v78
	v_add_f32_e32 v76, v90, v76
	v_cvt_pk_bf16_f32 v88, v88, v89
	v_cvt_pk_bf16_f32 v89, v86, v87
	global_store_dwordx2 v[84:85], v[88:89], off offset:288
	v_cndmask_b32_e32 v77, v190, v77, vcc
	v_lshlrev_b32_e32 v77, 2, v77
	ds_bpermute_b32 v77, v77, v76
	s_waitcnt lgkmcnt(0)
	v_add_f32_e32 v76, v76, v77
	v_xor_b32_e32 v77, 32, v190
	v_cmp_lt_i32_e32 vcc, v77, v78
	s_nop 1
	v_cndmask_b32_e32 v77, v190, v77, vcc
	v_lshlrev_b32_e32 v77, 2, v77
	ds_bpermute_b32 v77, v77, v76
	s_and_saveexec_b64 s[14:15], s[38:39]
	s_cbranch_execz .LBB0_821
	v_readlane_b32 s16, v245, 42
	v_readlane_b32 s17, v245, 43
	s_waitcnt lgkmcnt(0)
	v_add_f32_e32 v76, v76, v77
	v_lshl_add_u64 v[78:79], v[82:83], 2, s[16:17]
	global_atomic_add_f32 v[78:79], v76, off

; __device__ __forceinline__ unsigned cvt_pk_bf16(float lo, float hi) { unsigned r; asm volatile("v_cvt_pk_bf16_f32 %0, %1, %2" : "=v"(r) : "v"(lo), "v"(hi)); return r; }
;     __device__ __forceinline__ void operator()(const f32x4 (&acc)[2][2][4][2], const Unit& u, int wr, int wc, int fr, int fq) const {
;     ...
;                 const size_t off = (size_t)row * 1024 + col0;
;                 float sq = 0.f;
; #pragma unroll
;                 for (int bj = 0; bj < 2; ++bj)
; #pragma unroll
;                     for (int n = 0; n < 2; ++n) {
;                         const f32x4 b = *(const f32x4*)(base + off + bj * HALF + n * 16); const f32x4 o = b + acc[ai][bj][m][n];
;                         *(f32x4*)(out + off + bj * HALF + n * 16) = o;
;                         if (xn) { sq += (o[0] * o[0] + o[1] * o[1]) + (o[2] * o[2] + o[3] * o[3]); const f32x4 og = o * gv[bj][n];
;                             ::u32x2 w; w.x = cvt_pk_bf16(og[0], og[1]); w.y = cvt_pk_bf16(og[2], og[3]); *(::u32x2*)(xn + off + bj * HALF + n * 16) = w; }
;                     }
;                 if (xn) { sq += __shfl_xor(sq, 16); sq += __shfl_xor(sq, 32); if (fq == 0) atomicAdd(ss + row, sq); }
.LBB0_822:
	s_andn2_b64 vcc, exec, s[14:15]
	s_cbranch_vccnz .LBB0_824
	s_waitcnt lgkmcnt(0)
	s_waitcnt vmcnt(3)
	v_pk_add_f32 v[74:75], v[74:75], v[214:215]
	v_pk_add_f32 v[72:73], v[72:73], v[212:213]
	global_store_dwordx4 v[80:81], v[72:75], off offset:64
	s_waitcnt vmcnt(3)
	v_pk_add_f32 v[70:71], v[70:71], v[218:219]
	v_pk_add_f32 v[68:69], v[68:69], v[216:217]
	global_store_dwordx4 v[80:81], v[68:71], off offset:512
	s_waitcnt vmcnt(3)
	v_pk_add_f32 v[66:67], v[66:67], v[222:223]
	v_pk_add_f32 v[64:65], v[64:65], v[220:221]
	global_store_dwordx4 v[80:81], v[64:67], off offset:576
.LBB0_824:
	s_nop 1
	v_add_u32_e32 v66, 0x90, v168
	v_ashrrev_i32_e32 v67, 31, v66
	v_lshlrev_b64 v[64:65], 10, v[66:67]
	v_readlane_b32 s44, v249, 0
	v_lshl_add_u64 v[68:69], v[64:65], 0, v[152:153]
	v_readlane_b32 s46, v249, 2
	v_readlane_b32 s47, v249, 3
	s_and_b64 vcc, exec, s[42:43]
	s_mov_b64 s[14:15], -1
	v_lshl_add_u64 v[64:65], v[68:69], 2, s[46:47]
	global_load_dwordx4 v[70:73], v[64:65], off
	global_load_dwordx4 v[212:215], v[64:65], off offset:64
	global_load_dwordx4 v[216:219], v[64:65], off offset:512
	global_load_dwordx4 v[220:223], v[64:65], off offset:576
	v_readlane_b32 s45, v249, 1
	v_readlane_b32 s48, v249, 4
	v_readlane_b32 s49, v249, 5
	v_readlane_b32 s50, v249, 6
	v_readlane_b32 s51, v249, 7
	s_waitcnt vmcnt(3)
	v_pk_add_f32 v[62:63], v[62:63], v[72:73]
	v_pk_add_f32 v[60:61], v[60:61], v[70:71]
	global_store_dwordx4 v[64:65], v[60:63], off
	s_cbranch_vccnz .LBB0_828
	v_readlane_b32 s14, v245, 28
	v_mul_f32_e32 v70, v61, v61
	v_readlane_b32 s15, v245, 29
	v_fmac_f32_e32 v70, v60, v60
	v_mul_f32_e32 v71, v63, v63
	v_pk_mul_f32 v[60:61], v[56:57], v[60:61]
	v_lshl_add_u64 v[68:69], v[68:69], 1, s[14:15]
	v_fmac_f32_e32 v71, v62, v62
	v_pk_mul_f32 v[62:63], v[58:59], v[62:63]
	v_cvt_pk_bf16_f32 v60, v60, v61
	v_add_f32_e32 v70, v70, v71
	v_cvt_pk_bf16_f32 v61, v62, v63
	global_store_dwordx2 v[68:69], v[60:61], off
	s_waitcnt vmcnt(4)
	v_pk_add_f32 v[60:61], v[44:45], v[212:213]
	v_pk_add_f32 v[62:63], v[46:47], v[214:215]
	v_mul_f32_e32 v71, v61, v61
	global_store_dwordx4 v[64:65], v[60:63], off offset:64
	v_fmac_f32_e32 v71, v60, v60
	v_mul_f32_e32 v72, v63, v63
	v_pk_mul_f32 v[60:61], v[52:53], v[60:61]
	v_fmac_f32_e32 v72, v62, v62
	v_pk_mul_f32 v[62:63], v[54:55], v[62:63]
	v_cvt_pk_bf16_f32 v60, v60, v61
	v_add_f32_e32 v71, v71, v72
	v_cvt_pk_bf16_f32 v61, v62, v63
	global_store_dwordx2 v[68:69], v[60:61], off offset:32
	v_add_f32_e32 v70, v70, v71
	s_waitcnt vmcnt(5)
	v_pk_add_f32 v[60:61], v[40:41], v[216:217]
	v_pk_add_f32 v[62:63], v[42:43], v[218:219]
	v_mul_f32_e32 v71, v61, v61
	global_store_dwordx4 v[64:65], v[60:63], off offset:512
	v_fmac_f32_e32 v71, v60, v60
	v_mul_f32_e32 v72, v63, v63
	v_pk_mul_f32 v[60:61], v[48:49], v[60:61]
	v_fmac_f32_e32 v72, v62, v62
	v_pk_mul_f32 v[62:63], v[50:51], v[62:63]
	v_cvt_pk_bf16_f32 v60, v60, v61
	v_add_f32_e32 v71, v71, v72
	v_cvt_pk_bf16_f32 v61, v62, v63
	global_store_dwordx2 v[68:69], v[60:61], off offset:256
	v_add_f32_e32 v74, v70, v71
	s_waitcnt vmcnt(6)
	v_pk_add_f32 v[62:63], v[34:35], v[222:223]
	v_pk_add_f32 v[60:61], v[32:33], v[220:221]
	global_store_dwordx4 v[64:65], v[60:63], off offset:576
	v_pk_mul_f32 v[72:73], v[36:37], v[60:61]
	v_pk_mul_f32 v[70:71], v[38:39], v[62:63]
	v_mul_f32_e32 v61, v61, v61
	v_fmac_f32_e32 v61, v60, v60
	v_mul_f32_e32 v60, v63, v63
	v_fmac_f32_e32 v60, v62, v62
	v_and_b32_e32 v62, 64, v190
	v_add_f32_e32 v60, v61, v60
	v_xor_b32_e32 v61, 16, v190
	v_add_u32_e32 v62, 64, v62
	v_cmp_lt_i32_e32 vcc, v61, v62
	v_add_f32_e32 v60, v74, v60
	v_cvt_pk_bf16_f32 v72, v72, v73
	v_cvt_pk_bf16_f32 v73, v70, v71
	global_store_dwordx2 v[68:69], v[72:73], off offset:288
	v_cndmask_b32_e32 v61, v190, v61, vcc
	v_lshlrev_b32_e32 v61, 2, v61
	ds_bpermute_b32 v61, v61, v60
	s_waitcnt lgkmcnt(0)
	v_add_f32_e32 v60, v60, v61
	v_xor_b32_e32 v61, 32, v190
	v_cmp_lt_i32_e32 vcc, v61, v62
	s_nop 1
	v_cndmask_b32_e32 v61, v190, v61, vcc
	v_lshlrev_b32_e32 v61, 2, v61
	ds_bpermute_b32 v61, v61, v60
	s_and_saveexec_b64 s[14:15], s[38:39]
	s_cbranch_execz .LBB0_827
	v_readlane_b32 s16, v245, 42
	v_readlane_b32 s17, v245, 43
	s_waitcnt lgkmcnt(0)
	v_add_f32_e32 v60, v60, v61
	v_lshl_add_u64 v[62:63], v[66:67], 2, s[16:17]
	global_atomic_add_f32 v[62:63], v60, off

; __device__ __forceinline__ unsigned cvt_pk_bf16(float lo, float hi) { unsigned r; asm volatile("v_cvt_pk_bf16_f32 %0, %1, %2" : "=v"(r) : "v"(lo), "v"(hi)); return r; }
;     __device__ __forceinline__ void operator()(const f32x4 (&acc)[2][2][4][2], const Unit& u, int wr, int wc, int fr, int fq) const {
;     ...
;                 const size_t off = (size_t)row * 1024 + col0;
;                 float sq = 0.f;
; #pragma unroll
;                 for (int bj = 0; bj < 2; ++bj)
; #pragma unroll
;                     for (int n = 0; n < 2; ++n) {
;                         const f32x4 b = *(const f32x4*)(base + off + bj * HALF + n * 16); const f32x4 o = b + acc[ai][bj][m][n];
;                         *(f32x4*)(out + off + bj * HALF + n * 16) = o;
;                         if (xn) { sq += (o[0] * o[0] + o[1] * o[1]) + (o[2] * o[2] + o[3] * o[3]); const f32x4 og = o * gv[bj][n];
;                             ::u32x2 w; w.x = cvt_pk_bf16(og[0], og[1]); w.y = cvt_pk_bf16(og[2], og[3]); *(::u32x2*)(xn + off + bj * HALF + n * 16) = w; }
;                     }
;                 if (xn) { sq += __shfl_xor(sq, 16); sq += __shfl_xor(sq, 32); if (fq == 0) atomicAdd(ss + row, sq); }
.LBB0_828:
	s_andn2_b64 vcc, exec, s[14:15]
	s_cbranch_vccnz .LBB0_830
	s_waitcnt lgkmcnt(0)
	s_waitcnt vmcnt(3)
	v_pk_add_f32 v[46:47], v[46:47], v[214:215]
	v_pk_add_f32 v[44:45], v[44:45], v[212:213]
	global_store_dwordx4 v[64:65], v[44:47], off offset:64
	s_waitcnt vmcnt(3)
	v_pk_add_f32 v[42:43], v[42:43], v[218:219]
	v_pk_add_f32 v[40:41], v[40:41], v[216:217]
	global_store_dwordx4 v[64:65], v[40:43], off offset:512
	s_waitcnt vmcnt(3)
	v_pk_add_f32 v[34:35], v[34:35], v[222:223]
	v_pk_add_f32 v[32:33], v[32:33], v[220:221]
	global_store_dwordx4 v[64:65], v[32:35], off offset:576
.LBB0_830:
	s_nop 1
	v_add_u32_e32 v34, 0xa0, v168
	v_ashrrev_i32_e32 v35, 31, v34
	v_lshlrev_b64 v[32:33], 10, v[34:35]
	v_readlane_b32 s44, v249, 0
	v_lshl_add_u64 v[40:41], v[32:33], 0, v[152:153]
	v_readlane_b32 s46, v249, 2
	v_readlane_b32 s47, v249, 3
	s_and_b64 vcc, exec, s[42:43]
	s_mov_b64 s[14:15], -1
	v_lshl_add_u64 v[32:33], v[40:41], 2, s[46:47]
	global_load_dwordx4 v[42:45], v[32:33], off
	global_load_dwordx4 v[212:215], v[32:33], off offset:64
	global_load_dwordx4 v[216:219], v[32:33], off offset:512
	global_load_dwordx4 v[220:223], v[32:33], off offset:576
	v_readlane_b32 s45, v249, 1
	v_readlane_b32 s48, v249, 4
	v_readlane_b32 s49, v249, 5
	v_readlane_b32 s50, v249, 6
	v_readlane_b32 s51, v249, 7
	s_waitcnt vmcnt(3)
	v_pk_add_f32 v[30:31], v[30:31], v[44:45]
	v_pk_add_f32 v[28:29], v[28:29], v[42:43]
	global_store_dwordx4 v[32:33], v[28:31], off
	s_cbranch_vccnz .LBB0_834
	v_readlane_b32 s14, v245, 28
	v_mul_f32_e32 v42, v29, v29
	v_readlane_b32 s15, v245, 29
	v_fmac_f32_e32 v42, v28, v28
	v_mul_f32_e32 v43, v31, v31
	v_pk_mul_f32 v[28:29], v[56:57], v[28:29]
	v_lshl_add_u64 v[40:41], v[40:41], 1, s[14:15]
	v_fmac_f32_e32 v43, v30, v30
	v_pk_mul_f32 v[30:31], v[58:59], v[30:31]
	v_cvt_pk_bf16_f32 v28, v28, v29
	v_add_f32_e32 v42, v42, v43
	v_cvt_pk_bf16_f32 v29, v30, v31
	global_store_dwordx2 v[40:41], v[28:29], off
	s_waitcnt vmcnt(4)
	v_pk_add_f32 v[28:29], v[24:25], v[212:213]
	v_pk_add_f32 v[30:31], v[26:27], v[214:215]
	v_mul_f32_e32 v43, v29, v29
	global_store_dwordx4 v[32:33], v[28:31], off offset:64
	v_fmac_f32_e32 v43, v28, v28
	v_mul_f32_e32 v44, v31, v31
	v_pk_mul_f32 v[28:29], v[52:53], v[28:29]
	v_fmac_f32_e32 v44, v30, v30
	v_pk_mul_f32 v[30:31], v[54:55], v[30:31]
	v_cvt_pk_bf16_f32 v28, v28, v29
	v_add_f32_e32 v43, v43, v44
	v_cvt_pk_bf16_f32 v29, v30, v31
	global_store_dwordx2 v[40:41], v[28:29], off offset:32
	v_add_f32_e32 v42, v42, v43
	s_waitcnt vmcnt(5)
	v_pk_add_f32 v[28:29], v[20:21], v[216:217]
	v_pk_add_f32 v[30:31], v[22:23], v[218:219]
	v_mul_f32_e32 v43, v29, v29
	global_store_dwordx4 v[32:33], v[28:31], off offset:512
	v_fmac_f32_e32 v43, v28, v28
	v_mul_f32_e32 v44, v31, v31
	v_pk_mul_f32 v[28:29], v[48:49], v[28:29]
	v_fmac_f32_e32 v44, v30, v30
	v_pk_mul_f32 v[30:31], v[50:51], v[30:31]
	v_cvt_pk_bf16_f32 v28, v28, v29
	v_add_f32_e32 v43, v43, v44
	v_cvt_pk_bf16_f32 v29, v30, v31
	global_store_dwordx2 v[40:41], v[28:29], off offset:256
	v_add_f32_e32 v46, v42, v43
	s_waitcnt vmcnt(6)
	v_pk_add_f32 v[30:31], v[18:19], v[222:223]
	v_pk_add_f32 v[28:29], v[16:17], v[220:221]
	global_store_dwordx4 v[32:33], v[28:31], off offset:576
	v_pk_mul_f32 v[44:45], v[36:37], v[28:29]
	v_pk_mul_f32 v[42:43], v[38:39], v[30:31]
	v_mul_f32_e32 v29, v29, v29
	v_fmac_f32_e32 v29, v28, v28
	v_mul_f32_e32 v28, v31, v31
	v_fmac_f32_e32 v28, v30, v30
	v_and_b32_e32 v30, 64, v190
	v_add_f32_e32 v28, v29, v28
	v_xor_b32_e32 v29, 16, v190
	v_add_u32_e32 v30, 64, v30
	v_cmp_lt_i32_e32 vcc, v29, v30
	v_add_f32_e32 v28, v46, v28
	v_cvt_pk_bf16_f32 v44, v44, v45
	v_cvt_pk_bf16_f32 v45, v42, v43
	global_store_dwordx2 v[40:41], v[44:45], off offset:288
	v_cndmask_b32_e32 v29, v190, v29, vcc
	v_lshlrev_b32_e32 v29, 2, v29
	ds_bpermute_b32 v29, v29, v28
	s_waitcnt lgkmcnt(0)
	v_add_f32_e32 v28, v28, v29
	v_xor_b32_e32 v29, 32, v190
	v_cmp_lt_i32_e32 vcc, v29, v30
	s_nop 1
	v_cndmask_b32_e32 v29, v190, v29, vcc
	v_lshlrev_b32_e32 v29, 2, v29
	ds_bpermute_b32 v29, v29, v28
	s_and_saveexec_b64 s[14:15], s[38:39]
	s_cbranch_execz .LBB0_833
	v_readlane_b32 s16, v245, 42
	v_readlane_b32 s17, v245, 43
	s_waitcnt lgkmcnt(0)
	v_add_f32_e32 v28, v28, v29
	v_lshl_add_u64 v[30:31], v[34:35], 2, s[16:17]
	global_atomic_add_f32 v[30:31], v28, off

; __device__ __forceinline__ unsigned cvt_pk_bf16(float lo, float hi) { unsigned r; asm volatile("v_cvt_pk_bf16_f32 %0, %1, %2" : "=v"(r) : "v"(lo), "v"(hi)); return r; }
;     __device__ __forceinline__ void operator()(const f32x4 (&acc)[2][2][4][2], const Unit& u, int wr, int wc, int fr, int fq) const {
;     ...
;                 const size_t off = (size_t)row * 1024 + col0;
;                 float sq = 0.f;
; #pragma unroll
;                 for (int bj = 0; bj < 2; ++bj)
; #pragma unroll
;                     for (int n = 0; n < 2; ++n) {
;                         const f32x4 b = *(const f32x4*)(base + off + bj * HALF + n * 16); const f32x4 o = b + acc[ai][bj][m][n];
;                         *(f32x4*)(out + off + bj * HALF + n * 16) = o;
;                         if (xn) { sq += (o[0] * o[0] + o[1] * o[1]) + (o[2] * o[2] + o[3] * o[3]); const f32x4 og = o * gv[bj][n];
;                             ::u32x2 w; w.x = cvt_pk_bf16(og[0], og[1]); w.y = cvt_pk_bf16(og[2], og[3]); *(::u32x2*)(xn + off + bj * HALF + n * 16) = w; }
;                     }
;                 if (xn) { sq += __shfl_xor(sq, 16); sq += __shfl_xor(sq, 32); if (fq == 0) atomicAdd(ss + row, sq); }
.LBB0_834:
	s_andn2_b64 vcc, exec, s[14:15]
	s_cbranch_vccnz .LBB0_836
	s_waitcnt lgkmcnt(0)
	s_waitcnt vmcnt(3)
	v_pk_add_f32 v[26:27], v[26:27], v[214:215]
	v_pk_add_f32 v[24:25], v[24:25], v[212:213]
	global_store_dwordx4 v[32:33], v[24:27], off offset:64
	s_waitcnt vmcnt(3)
	v_pk_add_f32 v[22:23], v[22:23], v[218:219]
	v_pk_add_f32 v[20:21], v[20:21], v[216:217]
	global_store_dwordx4 v[32:33], v[20:23], off offset:512
	s_waitcnt vmcnt(3)
	v_pk_add_f32 v[18:19], v[18:19], v[222:223]
	v_pk_add_f32 v[16:17], v[16:17], v[220:221]
	global_store_dwordx4 v[32:33], v[16:19], off offset:576
.LBB0_836:
	s_nop 1
	v_add_u32_e32 v18, 0xb0, v168
	v_ashrrev_i32_e32 v19, 31, v18
	v_lshlrev_b64 v[16:17], 10, v[18:19]
	v_readlane_b32 s44, v249, 0
	v_lshl_add_u64 v[20:21], v[16:17], 0, v[152:153]
	v_readlane_b32 s46, v249, 2
	v_readlane_b32 s47, v249, 3
	s_and_b64 vcc, exec, s[42:43]
	s_mov_b64 s[14:15], -1
	v_lshl_add_u64 v[16:17], v[20:21], 2, s[46:47]
	global_load_dwordx4 v[22:25], v[16:17], off
	global_load_dwordx4 v[212:215], v[16:17], off offset:64
	global_load_dwordx4 v[216:219], v[16:17], off offset:512
	global_load_dwordx4 v[220:223], v[16:17], off offset:576
	v_readlane_b32 s45, v249, 1
	v_readlane_b32 s48, v249, 4
	v_readlane_b32 s49, v249, 5
	v_readlane_b32 s50, v249, 6
	v_readlane_b32 s51, v249, 7
	s_waitcnt vmcnt(3)
	v_pk_add_f32 v[14:15], v[14:15], v[24:25]
	v_pk_add_f32 v[12:13], v[12:13], v[22:23]
	global_store_dwordx4 v[16:17], v[12:15], off
	s_cbranch_vccnz .LBB0_840
	v_readlane_b32 s14, v245, 28
	v_readlane_b32 s15, v245, 29
	v_pk_mul_f32 v[24:25], v[56:57], v[12:13]
	v_pk_mul_f32 v[22:23], v[58:59], v[14:15]
	v_lshl_add_u64 v[32:33], v[20:21], 1, s[14:15]
	v_cvt_pk_bf16_f32 v24, v24, v25
	v_cvt_pk_bf16_f32 v25, v22, v23
	global_store_dwordx2 v[32:33], v[24:25], off
	v_mul_f32_e32 v13, v13, v13
	v_mul_f32_e32 v15, v15, v15
	v_fmac_f32_e32 v13, v12, v12
	v_fmac_f32_e32 v15, v14, v14
	v_add_f32_e32 v13, v13, v15
	v_and_b32_e32 v35, 64, v190
	v_xor_b32_e32 v34, 16, v190
	v_add_u32_e32 v12, 64, v35
	v_cmp_lt_i32_e32 vcc, v34, v12
	v_xor_b32_e32 v40, 32, v190
	s_waitcnt vmcnt(4)
	v_pk_add_f32 v[20:21], v[8:9], v[212:213]
	v_pk_add_f32 v[22:23], v[10:11], v[214:215]
	v_pk_mul_f32 v[26:27], v[52:53], v[20:21]
	global_store_dwordx4 v[16:17], v[20:23], off offset:64
	v_pk_mul_f32 v[24:25], v[54:55], v[22:23]
	v_cvt_pk_bf16_f32 v26, v26, v27
	v_mul_f32_e32 v15, v21, v21
	v_cvt_pk_bf16_f32 v27, v24, v25
	global_store_dwordx2 v[32:33], v[26:27], off offset:32
	v_mul_f32_e32 v21, v23, v23
	v_fmac_f32_e32 v15, v20, v20
	v_fmac_f32_e32 v21, v22, v22
	v_add_f32_e32 v15, v15, v21
	v_add_f32_e32 v13, v13, v15
	v_cndmask_b32_e32 v14, v190, v34, vcc
	v_lshlrev_b32_e32 v14, 2, v14
	v_cmp_lt_i32_e32 vcc, v40, v12
	s_waitcnt vmcnt(5)
	v_pk_add_f32 v[24:25], v[4:5], v[216:217]
	v_pk_add_f32 v[26:27], v[6:7], v[218:219]
	v_pk_mul_f32 v[30:31], v[48:49], v[24:25]
	global_store_dwordx4 v[16:17], v[24:27], off offset:512
	s_waitcnt lgkmcnt(0)
	v_pk_mul_f32 v[28:29], v[50:51], v[26:27]
	v_cvt_pk_bf16_f32 v30, v30, v31
	v_mul_f32_e32 v15, v25, v25
	v_cvt_pk_bf16_f32 v31, v28, v29
	global_store_dwordx2 v[32:33], v[30:31], off offset:256
	v_mul_f32_e32 v20, v27, v27
	v_fmac_f32_e32 v15, v24, v24
	v_fmac_f32_e32 v20, v26, v26
	v_add_f32_e32 v15, v15, v20
	v_add_f32_e32 v13, v13, v15
	v_cndmask_b32_e32 v25, v190, v40, vcc
	s_waitcnt vmcnt(6)
	v_pk_add_f32 v[22:23], v[2:3], v[222:223]
	v_pk_add_f32 v[20:21], v[0:1], v[220:221]
	v_mul_f32_e32 v24, v23, v23
	v_mul_f32_e32 v15, v21, v21
	v_fmac_f32_e32 v15, v20, v20
	v_fmac_f32_e32 v24, v22, v22
	v_add_f32_e32 v15, v15, v24
	v_add_f32_e32 v13, v13, v15
	ds_bpermute_b32 v24, v14, v13
	global_store_dwordx4 v[16:17], v[20:23], off offset:576
	v_pk_mul_f32 v[14:15], v[38:39], v[22:23]
	s_waitcnt lgkmcnt(0)
	v_add_f32_e32 v12, v13, v24
	v_lshlrev_b32_e32 v13, 2, v25
	ds_bpermute_b32 v13, v13, v12
	v_pk_mul_f32 v[20:21], v[36:37], v[20:21]
	s_nop 0
	v_cvt_pk_bf16_f32 v20, v20, v21
	v_cvt_pk_bf16_f32 v21, v14, v15
	global_store_dwordx2 v[32:33], v[20:21], off offset:288
	s_and_saveexec_b64 s[14:15], s[38:39]
	s_cbranch_execz .LBB0_839
	v_readlane_b32 s16, v245, 42
	v_readlane_b32 s17, v245, 43
	s_waitcnt lgkmcnt(0)
	v_add_f32_e32 v12, v12, v13
	v_lshl_add_u64 v[14:15], v[18:19], 2, s[16:17]
	global_atomic_add_f32 v[14:15], v12, off

;     __device__ __forceinline__ void operator()(const f32x4 (&acc)[2][2][4][2], const Unit& u, int wr, int wc, int fr, int fq) const {
;     ...
;                 const size_t off = (size_t)row * 1024 + col0;
;                 float sq = 0.f;
; #pragma unroll
;                 for (int bj = 0; bj < 2; ++bj)
; #pragma unroll
;                     for (int n = 0; n < 2; ++n) {
;                         const f32x4 b = *(const f32x4*)(base + off + bj * HALF + n * 16); const f32x4 o = b + acc[ai][bj][m][n];
;                         *(f32x4*)(out + off + bj * HALF + n * 16) = o;
.LBB0_840:
	s_andn2_b64 vcc, exec, s[14:15]
	s_cbranch_vccnz .LBB0_842
	s_waitcnt lgkmcnt(0)
	s_waitcnt vmcnt(3)
	v_pk_add_f32 v[10:11], v[10:11], v[214:215]
	v_pk_add_f32 v[8:9], v[8:9], v[212:213]
	global_store_dwordx4 v[16:17], v[8:11], off offset:64
	s_waitcnt vmcnt(3)
	v_pk_add_f32 v[6:7], v[6:7], v[218:219]
	v_pk_add_f32 v[4:5], v[4:5], v[216:217]
	global_store_dwordx4 v[16:17], v[4:7], off offset:512
	s_waitcnt vmcnt(3)
	v_pk_add_f32 v[2:3], v[2:3], v[222:223]
	v_pk_add_f32 v[0:1], v[0:1], v[220:221]
	global_store_dwordx4 v[16:17], v[0:3], off offset:576
